# moba_bucket attention tile: row max taken over the raw QK^T MFMA results (max(c*s)=c*max(s) exactly, c>0) with four independent v_max3 accumulators, scaled once - removes 63 v_mul per lane per tile
# speedup vs baseline: 1.0324x; 1.0066x over previous
.LBB0_1474:
	s_ashr_i32 s12, s14, 7
	s_ashr_i32 s13, s12, 31
	v_ashrrev_i32_e32 v40, 4, v53
	s_lshl_b64 s[22:23], s[12:13], 14
	v_ashrrev_i32_e32 v41, 31, v40
	v_lshl_add_u64 v[0:1], s[22:23], 0, v[40:41]
	s_bfe_u32 s11, s14, 0x10006
	v_mad_u64_u32 v[2:3], s[24:25], v0, s16, v[38:39]
	s_lshl_b32 s14, s14, 8
	s_and_b32 s24, s14, 0x3f00
	s_or_b32 s14, s22, s24
	s_mul_i32 s15, s23, 0xc00
	s_mul_hi_u32 s22, s14, 0xc00
	s_add_i32 s22, s22, s15
	s_mulk_i32 s14, 0xc00
	s_add_u32 s14, s76, s14
	s_addc_u32 s15, s77, s22
	s_lshl_b32 s22, s11, 7
	v_lshlrev_b32_e32 v0, 5, v53
	s_add_u32 s22, s14, s22
	v_and_b32_e32 v0, 0x180, v0
	s_addc_u32 s23, s15, 0
	s_lshl_b32 s14, s12, 1
	v_mad_i32_i24 v3, v1, s16, v3
	v_lshl_or_b32 v36, s11, 9, v0
	s_or_b32 s14, s14, s11
	v_mov_b32_e32 v58, v128
	v_lshl_add_u64 v[88:89], v[2:3], 0, v[36:37]
	s_add_i32 s14, s14, 4
	s_ashr_i32 s15, s14, 31
	v_lshlrev_b32_e32 v2, 4, v58
	v_add_u32_e32 v12, 0x100, v58
	v_and_b32_e32 v36, 0x70, v2
	v_ashrrev_i32_e32 v2, 31, v58
	v_ashrrev_i32_e32 v10, 31, v12
	v_add_u32_e32 v57, 0x400, v58
	s_lshl_b64 s[14:15], s[14:15], 21
	v_lshrrev_b32_e32 v2, 27, v2
	v_lshrrev_b32_e32 v10, 27, v10
	v_ashrrev_i32_e32 v34, 31, v57
	s_add_u32 s14, s80, s14
	v_add_u32_e32 v2, v58, v2
	v_add_u32_e32 v10, v12, v10
	v_lshrrev_b32_e32 v34, 27, v34
	s_addc_u32 s15, s81, s15
	s_lshl_b32 s24, s24, 1
	v_ashrrev_i32_e32 v96, 5, v2
	v_ashrrev_i32_e32 v100, 5, v10
	v_add_u32_e32 v34, v57, v34
	s_add_u32 s14, s14, s24
	v_lshlrev_b32_e32 v4, 3, v58
	v_ashrrev_i32_e32 v97, 31, v96
	v_lshlrev_b32_e32 v5, 8, v96
	v_ashrrev_i32_e32 v101, 31, v100
	v_ashrrev_i32_e32 v112, 5, v34
	s_addc_u32 s15, s15, 0
	v_ashrrev_i32_e32 v44, 3, v58
	v_mov_b64_e32 v[42:43], s[22:23]
	v_lshlrev_b64 v[2:3], 15, v[96:97]
	v_sub_u32_e32 v98, v4, v5
	v_lshlrev_b64 v[10:11], 15, v[100:101]
	v_add_u32_e32 v20, 0x200, v58
	v_ashrrev_i32_e32 v101, 3, v57
	v_lshlrev_b32_e32 v60, 8, v112
	v_lshlrev_b32_e32 v57, 3, v57
	v_mad_i64_i32 v[0:1], s[22:23], v44, s16, v[42:43]
	v_lshl_add_u64 v[2:3], s[14:15], 0, v[2:3]
	v_ashrrev_i32_e32 v99, 31, v98
	v_ashrrev_i32_e32 v18, 31, v20
	v_sub_u32_e32 v114, v57, v60
	v_add_u32_e32 v57, 0x500, v58
	v_lshl_add_u64 v[0:1], v[0:1], 0, v[36:37]
	v_lshl_add_u64 v[4:5], v[98:99], 1, v[2:3]
	v_ashrrev_i32_e32 v59, 3, v12
	v_lshlrev_b32_e32 v13, 8, v100
	v_lshlrev_b32_e32 v12, 3, v12
	v_lshrrev_b32_e32 v18, 27, v18
	v_ashrrev_i32_e32 v66, 31, v57
	global_load_dwordx4 v[0:3], v[0:1], off offset:2560
	s_nop 0
	global_load_dwordx4 v[4:7], v[4:5], off
	v_sub_u32_e32 v102, v12, v13
	v_add_u32_e32 v18, v20, v18
	v_add_u32_e32 v28, 0x300, v58
	v_lshrrev_b32_e32 v66, 27, v66
	v_mad_i64_i32 v[8:9], s[22:23], v59, s16, v[42:43]
	v_lshl_add_u64 v[10:11], s[14:15], 0, v[10:11]
	v_ashrrev_i32_e32 v103, 31, v102
	v_ashrrev_i32_e32 v104, 5, v18
	v_ashrrev_i32_e32 v26, 31, v28
	v_add_u32_e32 v66, v57, v66
	v_lshl_add_u64 v[8:9], v[8:9], 0, v[36:37]
	v_lshl_add_u64 v[12:13], v[102:103], 1, v[10:11]
	v_ashrrev_i32_e32 v97, 3, v20
	v_ashrrev_i32_e32 v105, 31, v104
	v_lshlrev_b32_e32 v21, 8, v104
	v_lshlrev_b32_e32 v20, 3, v20
	v_lshrrev_b32_e32 v26, 27, v26
	v_ashrrev_i32_e32 v116, 5, v66
	global_load_dwordx4 v[8:11], v[8:9], off offset:2560
	s_nop 0
	global_load_dwordx4 v[12:15], v[12:13], off
	v_lshlrev_b64 v[18:19], 15, v[104:105]
	v_sub_u32_e32 v106, v20, v21
	v_add_u32_e32 v26, v28, v26
	v_ashrrev_i32_e32 v103, 3, v57
	v_lshlrev_b32_e32 v68, 8, v116
	v_lshlrev_b32_e32 v57, 3, v57
	s_waitcnt lgkmcnt(0)
	v_mad_i64_i32 v[16:17], s[22:23], v97, s16, v[42:43]
	v_lshl_add_u64 v[18:19], s[14:15], 0, v[18:19]
	v_ashrrev_i32_e32 v107, 31, v106
	v_ashrrev_i32_e32 v108, 5, v26
	v_sub_u32_e32 v118, v57, v68
	v_add_u32_e32 v57, 0x600, v58
	v_lshl_add_u64 v[16:17], v[16:17], 0, v[36:37]
	v_lshl_add_u64 v[20:21], v[106:107], 1, v[18:19]
	v_ashrrev_i32_e32 v99, 3, v28
	v_ashrrev_i32_e32 v109, 31, v108
	v_lshlrev_b32_e32 v29, 8, v108
	v_lshlrev_b32_e32 v28, 3, v28
	v_ashrrev_i32_e32 v74, 31, v57
	global_load_dwordx4 v[16:19], v[16:17], off offset:2560
	s_nop 0
	global_load_dwordx4 v[20:23], v[20:21], off
	v_lshlrev_b64 v[26:27], 15, v[108:109]
	v_sub_u32_e32 v110, v28, v29
	v_lshrrev_b32_e32 v74, 27, v74
	v_mad_i64_i32 v[24:25], s[22:23], v99, s16, v[42:43]
	v_lshl_add_u64 v[26:27], s[14:15], 0, v[26:27]
	v_ashrrev_i32_e32 v111, 31, v110
	v_add_u32_e32 v74, v57, v74
	v_lshl_add_u64 v[24:25], v[24:25], 0, v[36:37]
	v_lshl_add_u64 v[28:29], v[110:111], 1, v[26:27]
	v_ashrrev_i32_e32 v113, 31, v112
	v_ashrrev_i32_e32 v120, 5, v74
	global_load_dwordx4 v[24:27], v[24:25], off offset:2560
	s_nop 0
	global_load_dwordx4 v[28:31], v[28:29], off
	v_lshlrev_b64 v[34:35], 15, v[112:113]
	v_ashrrev_i32_e32 v105, 3, v57
	v_lshlrev_b32_e32 v76, 8, v120
	v_lshlrev_b32_e32 v57, 3, v57
	v_mad_i64_i32 v[32:33], s[22:23], v101, s16, v[42:43]
	v_lshl_add_u64 v[34:35], s[14:15], 0, v[34:35]
	v_ashrrev_i32_e32 v115, 31, v114
	v_ashrrev_i32_e32 v117, 31, v116
	v_ashrrev_i32_e32 v121, 31, v120
	v_sub_u32_e32 v122, v57, v76
	v_add_u32_e32 v57, 0x700, v58
	v_lshl_add_u64 v[32:33], v[32:33], 0, v[36:37]
	v_lshl_add_u64 v[60:61], v[114:115], 1, v[34:35]
	v_lshlrev_b64 v[66:67], 15, v[116:117]
	v_lshlrev_b64 v[74:75], 15, v[120:121]
	v_ashrrev_i32_e32 v107, 3, v57
	global_load_dwordx4 v[32:35], v[32:33], off offset:2560
	s_nop 0
	global_load_dwordx4 v[60:63], v[60:61], off
	v_mad_i64_i32 v[64:65], s[22:23], v103, s16, v[42:43]
	v_lshl_add_u64 v[66:67], s[14:15], 0, v[66:67]
	v_ashrrev_i32_e32 v119, 31, v118
	v_mad_i64_i32 v[72:73], s[22:23], v105, s16, v[42:43]
	v_lshl_add_u64 v[74:75], s[14:15], 0, v[74:75]
	v_ashrrev_i32_e32 v123, 31, v122
	v_mad_i64_i32 v[42:43], s[22:23], v107, s16, v[42:43]
	v_lshl_add_u64 v[64:65], v[64:65], 0, v[36:37]
	v_lshl_add_u64 v[68:69], v[118:119], 1, v[66:67]
	v_lshl_add_u64 v[72:73], v[72:73], 0, v[36:37]
	v_lshl_add_u64 v[76:77], v[122:123], 1, v[74:75]
	v_lshl_add_u64 v[42:43], v[42:43], 0, v[36:37]
	global_load_dwordx4 v[64:67], v[64:65], off offset:2560
	s_nop 0
	global_load_dwordx4 v[68:71], v[68:69], off
	s_nop 0
	global_load_dwordx4 v[72:75], v[72:73], off offset:2560
	s_nop 0
	global_load_dwordx4 v[76:79], v[76:77], off
	v_cmp_lt_i32_e32 vcc, v49, v50
	global_load_dwordx4 v[80:83], v[42:43], off offset:2560
	v_ashrrev_i32_e32 v42, 31, v57
	v_lshrrev_b32_e32 v42, 27, v42
	v_add_u32_e32 v42, v57, v42
	v_ashrrev_i32_e32 v124, 5, v42
	v_ashrrev_i32_e32 v125, 31, v124
	v_lshlrev_b32_e32 v84, 8, v124
	v_lshlrev_b32_e32 v57, 3, v57
	v_lshlrev_b64 v[42:43], 15, v[124:125]
	v_sub_u32_e32 v126, v57, v84
	v_lshl_add_u64 v[42:43], s[14:15], 0, v[42:43]
	v_ashrrev_i32_e32 v127, 31, v126
	v_lshl_add_u64 v[42:43], v[126:127], 1, v[42:43]
	global_load_dwordx4 v[84:87], v[42:43], off
	v_bfe_u32 v57, v58, 4, 2
	v_lshlrev_b32_e32 v42, 4, v57
	v_mov_b32_e32 v43, v37
	v_lshl_add_u64 v[92:93], v[88:89], 0, v[42:43]
	global_load_dwordx4 v[88:91], v[92:93], off offset:1536
	s_nop 0
	global_load_dwordx4 v[92:95], v[92:93], off offset:1600
	v_mad_u64_u32 v[130:131], s[14:15], v44, s17, v[36:37]
	s_barrier
	s_waitcnt vmcnt(17)
	ds_write_b128 v130, v[0:3]
	v_mul_lo_u32 v0, v96, s18
	v_lshl_add_u32 v0, v98, 1, v0
	s_waitcnt vmcnt(16)
	ds_write_b128 v0, v[4:7] offset:40960
	v_mad_u64_u32 v[0:1], s[14:15], v59, s17, v[36:37]
	s_waitcnt vmcnt(15)
	ds_write_b128 v0, v[8:11]
	v_mul_lo_u32 v0, v100, s18
	v_lshl_add_u32 v0, v102, 1, v0
	s_waitcnt vmcnt(14)
	ds_write_b128 v0, v[12:15] offset:40960
	v_mad_u64_u32 v[0:1], s[14:15], v97, s17, v[36:37]
	s_waitcnt vmcnt(13)
	ds_write_b128 v0, v[16:19]
	v_mul_lo_u32 v0, v104, s18
	v_lshl_add_u32 v0, v106, 1, v0
	s_waitcnt vmcnt(12)
	ds_write_b128 v0, v[20:23] offset:40960
	v_mad_u64_u32 v[0:1], s[14:15], v99, s17, v[36:37]
	s_waitcnt vmcnt(11)
	ds_write_b128 v0, v[24:27]
	v_mul_lo_u32 v0, v108, s18
	v_lshl_add_u32 v0, v110, 1, v0
	s_waitcnt vmcnt(10)
	ds_write_b128 v0, v[28:31] offset:40960
	v_mad_u64_u32 v[0:1], s[14:15], v101, s17, v[36:37]
	v_and_b32_e32 v43, 15, v58
	s_waitcnt vmcnt(9)
	ds_write_b128 v0, v[32:35]
	v_mul_lo_u32 v0, v112, s18
	v_lshl_add_u32 v0, v114, 1, v0
	s_waitcnt vmcnt(8)
	ds_write_b128 v0, v[60:63] offset:40960
	v_mad_u64_u32 v[0:1], s[14:15], v103, s17, v[36:37]
	s_waitcnt vmcnt(7)
	ds_write_b128 v0, v[64:67]
	v_mul_lo_u32 v0, v116, s18
	v_lshl_add_u32 v0, v118, 1, v0
	s_waitcnt vmcnt(6)
	ds_write_b128 v0, v[68:71] offset:40960
	v_mad_u64_u32 v[0:1], s[14:15], v105, s17, v[36:37]
	s_waitcnt vmcnt(5)
	ds_write_b128 v0, v[72:75]
	v_mul_lo_u32 v0, v120, s18
	v_lshl_add_u32 v0, v122, 1, v0
	s_waitcnt vmcnt(4)
	ds_write_b128 v0, v[76:79] offset:40960
	v_mad_u64_u32 v[0:1], s[14:15], v107, s17, v[36:37]
	s_waitcnt vmcnt(3)
	ds_write_b128 v0, v[80:83]
	v_mul_lo_u32 v0, v124, s18
	v_lshl_add_u32 v0, v126, 1, v0
	v_mad_u32_u24 v36, v43, s17, v42
	v_mad_u32_u24 v42, v43, s18, v42
	s_waitcnt vmcnt(2)
	ds_write_b128 v0, v[84:87] offset:40960
	s_waitcnt lgkmcnt(0)
	s_barrier
	ds_read_b128 v[0:3], v36
	ds_read_b128 v[4:7], v36 offset:64
	s_waitcnt vmcnt(1) lgkmcnt(1)
	v_mfma_f32_16x16x32_bf16 v[0:3], v[0:3], v[88:91], 0
	ds_read_b128 v[8:11], v36 offset:2560
	ds_read_b128 v[96:99], v36 offset:35840
	s_waitcnt vmcnt(0) lgkmcnt(2)
	v_mfma_f32_16x16x32_bf16 v[60:63], v[4:7], v[92:95], v[0:3]
	s_nop 3
	ds_read_b128 v[0:3], v36 offset:2624
	s_waitcnt lgkmcnt(2)
	v_mfma_f32_16x16x32_bf16 v[4:7], v[8:11], v[88:91], 0
	ds_read_b128 v[8:11], v36 offset:5120
	s_waitcnt lgkmcnt(1)
	v_mfma_f32_16x16x32_bf16 v[64:67], v[0:3], v[92:95], v[4:7]
	ds_read_b128 v[0:3], v36 offset:5184
	s_waitcnt lgkmcnt(1)
	v_mfma_f32_16x16x32_bf16 v[4:7], v[8:11], v[88:91], 0
	ds_read_b128 v[8:11], v36 offset:7680
	s_waitcnt lgkmcnt(1)
	v_mfma_f32_16x16x32_bf16 v[68:71], v[0:3], v[92:95], v[4:7]
	ds_read_b128 v[0:3], v36 offset:7744
	s_waitcnt lgkmcnt(1)
	v_mfma_f32_16x16x32_bf16 v[4:7], v[8:11], v[88:91], 0
	ds_read_b128 v[8:11], v36 offset:10240
	s_waitcnt lgkmcnt(1)
	v_mfma_f32_16x16x32_bf16 v[72:75], v[0:3], v[92:95], v[4:7]
	ds_read_b128 v[0:3], v36 offset:10304
	s_waitcnt lgkmcnt(1)
	v_mfma_f32_16x16x32_bf16 v[4:7], v[8:11], v[88:91], 0
	ds_read_b128 v[8:11], v36 offset:12800
	s_waitcnt lgkmcnt(1)
	v_mfma_f32_16x16x32_bf16 v[76:79], v[0:3], v[92:95], v[4:7]
	ds_read_b128 v[0:3], v36 offset:12864
	s_waitcnt lgkmcnt(1)
	v_mfma_f32_16x16x32_bf16 v[4:7], v[8:11], v[88:91], 0
	ds_read_b128 v[8:11], v36 offset:15360
	s_waitcnt lgkmcnt(1)
	v_mfma_f32_16x16x32_bf16 v[80:83], v[0:3], v[92:95], v[4:7]
	ds_read_b128 v[0:3], v36 offset:15424
	s_waitcnt lgkmcnt(1)
	v_mfma_f32_16x16x32_bf16 v[4:7], v[8:11], v[88:91], 0
	ds_read_b128 v[8:11], v36 offset:17920
	s_waitcnt lgkmcnt(1)
	v_mfma_f32_16x16x32_bf16 v[84:87], v[0:3], v[92:95], v[4:7]
	ds_read_b128 v[0:3], v36 offset:17984
	s_waitcnt lgkmcnt(1)
	v_mfma_f32_16x16x32_bf16 v[4:7], v[8:11], v[88:91], 0
	ds_read_b128 v[8:11], v36 offset:20480
	s_waitcnt lgkmcnt(1)
	v_mfma_f32_16x16x32_bf16 v[32:35], v[0:3], v[92:95], v[4:7]
	ds_read_b128 v[0:3], v36 offset:20544
	s_waitcnt lgkmcnt(1)
	v_mfma_f32_16x16x32_bf16 v[4:7], v[8:11], v[88:91], 0
	ds_read_b128 v[8:11], v36 offset:23040
	s_waitcnt lgkmcnt(1)
	v_mfma_f32_16x16x32_bf16 v[28:31], v[0:3], v[92:95], v[4:7]
	ds_read_b128 v[0:3], v36 offset:23104
	s_waitcnt lgkmcnt(1)
	v_mfma_f32_16x16x32_bf16 v[4:7], v[8:11], v[88:91], 0
	ds_read_b128 v[8:11], v36 offset:25600
	s_waitcnt lgkmcnt(1)
	v_mfma_f32_16x16x32_bf16 v[24:27], v[0:3], v[92:95], v[4:7]
	ds_read_b128 v[0:3], v36 offset:25664
	s_waitcnt lgkmcnt(1)
	v_mfma_f32_16x16x32_bf16 v[4:7], v[8:11], v[88:91], 0
	ds_read_b128 v[8:11], v36 offset:28160
	s_waitcnt lgkmcnt(1)
	v_mfma_f32_16x16x32_bf16 v[20:23], v[0:3], v[92:95], v[4:7]
	ds_read_b128 v[0:3], v36 offset:28224
	s_waitcnt lgkmcnt(1)
	v_mfma_f32_16x16x32_bf16 v[4:7], v[8:11], v[88:91], 0
	ds_read_b128 v[8:11], v36 offset:30720
	s_waitcnt lgkmcnt(1)
	v_mfma_f32_16x16x32_bf16 v[16:19], v[0:3], v[92:95], v[4:7]
	ds_read_b128 v[0:3], v36 offset:30784
	s_waitcnt lgkmcnt(1)
	v_mfma_f32_16x16x32_bf16 v[4:7], v[8:11], v[88:91], 0
	ds_read_b128 v[8:11], v36 offset:33280
	s_waitcnt lgkmcnt(1)
	v_mfma_f32_16x16x32_bf16 v[12:15], v[0:3], v[92:95], v[4:7]
	ds_read_b128 v[0:3], v36 offset:33344
	s_waitcnt lgkmcnt(1)
	v_mfma_f32_16x16x32_bf16 v[4:7], v[8:11], v[88:91], 0
	s_waitcnt lgkmcnt(0)
	v_mfma_f32_16x16x32_bf16 v[8:11], v[0:3], v[92:95], v[4:7]
	ds_read_b128 v[0:3], v36 offset:35904
	v_mfma_f32_16x16x32_bf16 v[4:7], v[96:99], v[88:91], 0
	ds_read_b128 v[96:99], v36 offset:38400
	s_waitcnt lgkmcnt(1)
	v_mfma_f32_16x16x32_bf16 v[4:7], v[0:3], v[92:95], v[4:7]
	ds_read_b128 v[0:3], v36 offset:38464
	v_max3_f32 v36, v60, s20, v61
	v_max_f32_e32 v44, v62, v63
	v_max_f32_e32 v59, v64, v65
	v_max_f32_e32 v152, v66, v67
	v_max3_f32 v36, v36, v68, v69
	v_max3_f32 v44, v44, v70, v71
	v_max3_f32 v59, v59, v72, v73
	v_max3_f32 v152, v152, v74, v75
	v_max3_f32 v36, v36, v76, v77
	v_max3_f32 v44, v44, v78, v79
	v_max3_f32 v59, v59, v80, v81
	v_max3_f32 v152, v152, v82, v83
	v_max3_f32 v36, v36, v84, v85
	v_max3_f32 v44, v44, v86, v87
	v_max3_f32 v59, v59, v32, v33
	v_max3_f32 v152, v152, v34, v35
	v_max3_f32 v36, v36, v28, v29
	v_max3_f32 v44, v44, v30, v31
	v_max3_f32 v59, v59, v24, v25
	v_max3_f32 v152, v152, v26, v27
	v_max3_f32 v36, v36, v20, v21
	s_waitcnt lgkmcnt(1)
	v_mfma_f32_16x16x32_bf16 v[88:91], v[96:99], v[88:91], 0
	v_max3_f32 v44, v44, v22, v23
	v_max3_f32 v59, v59, v16, v17
	v_max3_f32 v152, v152, v18, v19
	v_max3_f32 v36, v36, v12, v13
	s_waitcnt lgkmcnt(0)
	v_mfma_f32_16x16x32_bf16 v[0:3], v[0:3], v[92:95], v[88:91]
	v_max3_f32 v44, v44, v14, v15
	v_max3_f32 v59, v59, v8, v9
	v_max3_f32 v152, v152, v10, v11
	v_max3_f32 v36, v36, v4, v5
	v_max3_f32 v44, v44, v6, v7
	s_nop 2
	v_max3_f32 v59, v59, v0, v1
	v_max3_f32 v152, v152, v2, v3
	v_max3_f32 v36, v36, v44, v59
	v_max_f32_e32 v36, v36, v152
	v_mul_f32_e32 v36, 0x3e38aa3b, v36
	v_max_f32_e32 v36, s20, v36
	v_cndmask_b32_e32 v44, v48, v49, vcc
	v_lshlrev_b32_e32 v88, 2, v44
	ds_bpermute_b32 v44, v88, v36
	v_cmp_lt_i32_e32 vcc, v51, v50
	s_waitcnt lgkmcnt(0)
	s_barrier
	v_max_f32_e32 v44, v44, v44
	v_max_f32_e32 v36, v36, v44
	v_cndmask_b32_e32 v44, v48, v51, vcc
	v_lshlrev_b32_e32 v89, 2, v44
	ds_bpermute_b32 v59, v89, v36
	v_lshlrev_b32_e32 v44, 3, v57
	s_waitcnt lgkmcnt(0)
	v_max_f32_e32 v59, v59, v59
	v_max_f32_e32 v36, v36, v59
	v_fma_f32 v59, v60, s19, -v36
	v_fma_f32 v60, v61, s19, -v36
	v_fma_f32 v61, v62, s19, -v36
	v_fma_f32 v63, v63, s19, -v36
	v_fma_f32 v64, v64, s19, -v36
	v_fma_f32 v65, v65, s19, -v36
	v_fma_f32 v66, v66, s19, -v36
	v_fma_f32 v67, v67, s19, -v36
	v_fma_f32 v32, v32, s19, -v36
	v_fma_f32 v0, v0, s19, -v36
	v_exp_f32_e32 v59, v59
	v_exp_f32_e32 v60, v60
	v_exp_f32_e32 v61, v61
	v_exp_f32_e32 v63, v63
	v_exp_f32_e32 v64, v64
	v_exp_f32_e32 v65, v65
	v_exp_f32_e32 v66, v66
	v_exp_f32_e32 v67, v67
	v_fma_f32 v68, v68, s19, -v36
	v_fma_f32 v69, v69, s19, -v36
	v_fma_f32 v70, v70, s19, -v36
	v_fma_f32 v71, v71, s19, -v36
	v_fma_f32 v72, v72, s19, -v36
	v_fma_f32 v73, v73, s19, -v36
	v_fma_f32 v74, v74, s19, -v36
	v_fma_f32 v75, v75, s19, -v36
	v_exp_f32_e32 v91, v32
	v_fma_f32 v32, v33, s19, -v36
	v_fma_f32 v28, v28, s19, -v36
	v_fma_f32 v24, v24, s19, -v36
	v_fma_f32 v4, v4, s19, -v36
	v_exp_f32_e32 v123, v0
	v_fma_f32 v0, v1, s19, -v36
	v_ashrrev_i32_e32 v62, 2, v58
	v_exp_f32_e32 v68, v68
	v_exp_f32_e32 v69, v69
	v_exp_f32_e32 v70, v70
	v_exp_f32_e32 v71, v71
	v_exp_f32_e32 v72, v72
	v_exp_f32_e32 v73, v73
	v_exp_f32_e32 v74, v74
	v_exp_f32_e32 v75, v75
	v_fma_f32 v76, v76, s19, -v36
	v_fma_f32 v77, v77, s19, -v36
	v_fma_f32 v78, v78, s19, -v36
	v_fma_f32 v79, v79, s19, -v36
	v_fma_f32 v80, v80, s19, -v36
	v_fma_f32 v81, v81, s19, -v36
	v_fma_f32 v82, v82, s19, -v36
	v_fma_f32 v83, v83, s19, -v36
	v_exp_f32_e32 v92, v32
	v_fma_f32 v32, v34, s19, -v36
	v_exp_f32_e32 v95, v28
	v_fma_f32 v28, v29, s19, -v36
	v_exp_f32_e32 v99, v24
	v_fma_f32 v24, v25, s19, -v36
	v_fma_f32 v20, v20, s19, -v36
	v_fma_f32 v16, v16, s19, -v36
	v_exp_f32_e32 v119, v4
	v_fma_f32 v4, v5, s19, -v36
	v_exp_f32_e32 v124, v0
	v_fma_f32 v0, v2, s19, -v36
	v_exp_f32_e32 v76, v76
	v_exp_f32_e32 v77, v77
	v_exp_f32_e32 v78, v78
	v_exp_f32_e32 v79, v79
	v_exp_f32_e32 v80, v80
	v_exp_f32_e32 v81, v81
	v_exp_f32_e32 v82, v82
	v_exp_f32_e32 v83, v83
	v_fma_f32 v84, v84, s19, -v36
	v_fma_f32 v85, v85, s19, -v36
	v_fma_f32 v86, v86, s19, -v36
	v_fma_f32 v87, v87, s19, -v36
	v_exp_f32_e32 v93, v32
	v_fma_f32 v32, v35, s19, -v36
	v_exp_f32_e32 v96, v28
	v_fma_f32 v28, v30, s19, -v36
	v_exp_f32_e32 v100, v24
	v_fma_f32 v24, v26, s19, -v36
	v_exp_f32_e32 v103, v20
	v_fma_f32 v20, v21, s19, -v36
	v_exp_f32_e32 v107, v16
	v_fma_f32 v16, v17, s19, -v36
	v_fma_f32 v12, v12, s19, -v36
	v_fma_f32 v8, v8, s19, -v36
	v_exp_f32_e32 v120, v4
	v_fma_f32 v4, v6, s19, -v36
	v_exp_f32_e32 v125, v0
	v_fma_f32 v0, v3, s19, -v36
	v_bfi_b32 v127, -16, v62, v58
	v_exp_f32_e32 v84, v84
	v_exp_f32_e32 v85, v85
	v_exp_f32_e32 v86, v86
	v_exp_f32_e32 v87, v87
	v_exp_f32_e32 v94, v32
	v_exp_f32_e32 v97, v28
	v_fma_f32 v28, v31, s19, -v36
	v_exp_f32_e32 v101, v24
	v_fma_f32 v24, v27, s19, -v36
	v_exp_f32_e32 v104, v20
	v_fma_f32 v20, v22, s19, -v36
	v_exp_f32_e32 v108, v16
	v_fma_f32 v16, v18, s19, -v36
	v_exp_f32_e32 v111, v12
	v_fma_f32 v12, v13, s19, -v36
	v_exp_f32_e32 v115, v8
	v_fma_f32 v8, v9, s19, -v36
	v_exp_f32_e32 v121, v4
	v_fma_f32 v4, v7, s19, -v36
	v_exp_f32_e32 v126, v0
	v_mul_lo_u32 v0, v127, s18
	v_exp_f32_e32 v98, v28
	v_exp_f32_e32 v102, v24
	v_exp_f32_e32 v105, v20
	v_fma_f32 v20, v23, s19, -v36
	v_exp_f32_e32 v109, v16
	v_fma_f32 v16, v19, s19, -v36
	v_exp_f32_e32 v112, v12
	v_fma_f32 v12, v14, s19, -v36
	v_exp_f32_e32 v116, v8
	v_fma_f32 v8, v10, s19, -v36
	v_exp_f32_e32 v122, v4
	v_or_b32_e32 v4, v0, v44
	v_cvt_pk_bf16_f32 v0, v59, v60
	v_cvt_pk_bf16_f32 v1, v61, v63
	v_cvt_pk_bf16_f32 v2, v64, v65
	v_cvt_pk_bf16_f32 v3, v66, v67
	v_exp_f32_e32 v106, v20
	v_exp_f32_e32 v110, v16
	v_exp_f32_e32 v113, v12
	v_fma_f32 v12, v15, s19, -v36
	v_exp_f32_e32 v117, v8
	v_fma_f32 v8, v11, s19, -v36
	ds_write2_b64 v4, v[0:1], v[2:3] offset1:4
	v_cvt_pk_bf16_f32 v0, v68, v69
	v_cvt_pk_bf16_f32 v1, v70, v71
	v_cvt_pk_bf16_f32 v2, v72, v73
	v_cvt_pk_bf16_f32 v3, v74, v75
	v_exp_f32_e32 v114, v12
	v_exp_f32_e32 v118, v8
	ds_write2_b64 v4, v[0:1], v[2:3] offset0:8 offset1:12
	v_cvt_pk_bf16_f32 v0, v76, v77
	v_cvt_pk_bf16_f32 v1, v78, v79
	v_cvt_pk_bf16_f32 v2, v80, v81
	v_cvt_pk_bf16_f32 v3, v82, v83
	ds_write2_b64 v4, v[0:1], v[2:3] offset0:16 offset1:20
	v_cvt_pk_bf16_f32 v0, v84, v85
	v_cvt_pk_bf16_f32 v1, v86, v87
	v_cvt_pk_bf16_f32 v2, v91, v92
	v_cvt_pk_bf16_f32 v3, v93, v94
	ds_write2_b64 v4, v[0:1], v[2:3] offset0:24 offset1:28
	v_cvt_pk_bf16_f32 v0, v95, v96
	v_cvt_pk_bf16_f32 v1, v97, v98
	v_cvt_pk_bf16_f32 v2, v99, v100
	v_cvt_pk_bf16_f32 v3, v101, v102
	v_add_f32_e32 v90, 0, v59
	ds_write2_b64 v4, v[0:1], v[2:3] offset0:32 offset1:36
	v_cvt_pk_bf16_f32 v0, v103, v104
	v_cvt_pk_bf16_f32 v1, v105, v106
	v_cvt_pk_bf16_f32 v2, v107, v108
	v_cvt_pk_bf16_f32 v3, v109, v110
	v_add_f32_e32 v90, v60, v90
	ds_write2_b64 v4, v[0:1], v[2:3] offset0:40 offset1:44
	v_cvt_pk_bf16_f32 v0, v111, v112
	v_cvt_pk_bf16_f32 v1, v113, v114
	v_cvt_pk_bf16_f32 v2, v115, v116
	v_cvt_pk_bf16_f32 v3, v117, v118
	v_add_f32_e32 v90, v61, v90
	ds_write2_b64 v4, v[0:1], v[2:3] offset0:48 offset1:52
	v_cvt_pk_bf16_f32 v0, v119, v120
	v_cvt_pk_bf16_f32 v1, v121, v122
	v_cvt_pk_bf16_f32 v2, v123, v124
	v_cvt_pk_bf16_f32 v3, v125, v126
	v_add_f32_e32 v90, v63, v90
	ds_write2_b64 v4, v[0:1], v[2:3] offset0:56 offset1:60
	ds_read_b128 v[0:3], v42 offset:40960
	v_add_f32_e32 v90, v64, v90
	v_add_f32_e32 v90, v65, v90
	v_add_f32_e32 v90, v66, v90
	v_add_f32_e32 v12, v67, v90
	v_add_u32_e32 v43, v4, v44
	ds_read_b128 v[4:7], v43
	ds_read_b128 v[8:11], v42 offset:49664
	v_add_f32_e32 v32, v68, v12
	v_add_u32_e32 v66, 0x2200, v42
	ds_read_b128 v[12:15], v42 offset:58368
	ds_read_b128 v[16:19], v43 offset:64
	ds_read_b128 v[20:23], v42 offset:41024
	ds_read_b128 v[24:27], v66 offset:58368
	ds_read_b128 v[28:31], v42 offset:49728
	v_add_f32_e32 v32, v69, v32
	v_add_f32_e32 v58, v70, v32
	v_add_f32_e32 v58, v71, v58
	s_waitcnt lgkmcnt(6)
	v_mfma_f32_16x16x32_bf16 v[0:3], v[0:3], v[4:7], 0
	v_add_f32_e32 v62, v72, v58
	ds_read_b128 v[32:35], v42 offset:58432
	ds_read_b128 v[58:61], v66 offset:58432
	s_waitcnt lgkmcnt(7)
	v_mfma_f32_16x16x32_bf16 v[8:11], v[8:11], v[4:7], 0
	s_waitcnt lgkmcnt(6)
	v_mfma_f32_16x16x32_bf16 v[12:15], v[12:15], v[4:7], 0
	s_waitcnt lgkmcnt(3)
	v_mfma_f32_16x16x32_bf16 v[4:7], v[24:27], v[4:7], 0
	v_add_f32_e32 v24, v73, v62
	v_add_f32_e32 v24, v74, v24
	v_add_f32_e32 v24, v75, v24
	v_mfma_f32_16x16x32_bf16 v[0:3], v[20:23], v[16:19], v[0:3]
	v_add_f32_e32 v20, v76, v24
	v_add_f32_e32 v20, v77, v20
	v_add_f32_e32 v20, v78, v20
	v_add_f32_e32 v20, v79, v20
	v_add_f32_e32 v24, v80, v20
	ds_read_b128 v[20:23], v42 offset:41088
	s_waitcnt lgkmcnt(3)
	v_mfma_f32_16x16x32_bf16 v[8:11], v[28:31], v[16:19], v[8:11]
	v_add_f32_e32 v62, v81, v24
	ds_read_b128 v[24:27], v43 offset:128
	ds_read_b128 v[28:31], v42 offset:49792
	v_add_f32_e32 v67, v82, v62
	s_waitcnt lgkmcnt(4)
	v_mfma_f32_16x16x32_bf16 v[12:15], v[32:35], v[16:19], v[12:15]
	s_waitcnt lgkmcnt(3)
	v_mfma_f32_16x16x32_bf16 v[4:7], v[58:61], v[16:19], v[4:7]
	ds_read_b128 v[16:19], v42 offset:58496
	ds_read_b128 v[32:35], v43 offset:192
	ds_read_b128 v[58:61], v42 offset:41152
	s_waitcnt lgkmcnt(4)
	v_mfma_f32_16x16x32_bf16 v[0:3], v[20:23], v[24:27], v[0:3]
	ds_read_b128 v[20:23], v66 offset:58496
	ds_read_b128 v[62:65], v42 offset:49856
	s_waitcnt lgkmcnt(5)
	v_mfma_f32_16x16x32_bf16 v[8:11], v[28:31], v[24:27], v[8:11]
	v_add_f32_e32 v28, v83, v67
	v_add_f32_e32 v67, v84, v28
	ds_read_b128 v[28:31], v42 offset:58560
	s_waitcnt lgkmcnt(5)
	v_mfma_f32_16x16x32_bf16 v[12:15], v[16:19], v[24:27], v[12:15]
	v_add_f32_e32 v16, v85, v67
	v_add_f32_e32 v67, v86, v16
	ds_read_b128 v[16:19], v66 offset:58560
	s_waitcnt lgkmcnt(3)
	v_mfma_f32_16x16x32_bf16 v[4:7], v[20:23], v[24:27], v[4:7]
	v_add_f32_e32 v20, v87, v67
	v_add_f32_e32 v20, v91, v20
	v_add_f32_e32 v20, v92, v20
	v_add_f32_e32 v20, v93, v20
	v_add_f32_e32 v20, v94, v20
	v_add_f32_e32 v20, v95, v20
	v_add_f32_e32 v20, v96, v20
	v_add_f32_e32 v24, v97, v20
	ds_read_b128 v[20:23], v42 offset:41216
	s_waitcnt lgkmcnt(3)
	v_mfma_f32_16x16x32_bf16 v[8:11], v[62:65], v[32:35], v[8:11]
	v_add_f32_e32 v62, v98, v24
	v_add_f32_e32 v67, v99, v62
	s_waitcnt lgkmcnt(2)
	v_mfma_f32_16x16x32_bf16 v[12:15], v[28:31], v[32:35], v[12:15]
	ds_read_b128 v[24:27], v43 offset:256
	ds_read_b128 v[28:31], v42 offset:49920
	v_mfma_f32_16x16x32_bf16 v[0:3], v[58:61], v[32:35], v[0:3]
	s_waitcnt lgkmcnt(3)
	v_mfma_f32_16x16x32_bf16 v[4:7], v[16:19], v[32:35], v[4:7]
	ds_read_b128 v[16:19], v42 offset:58624
	ds_read_b128 v[32:35], v43 offset:320
	ds_read_b128 v[58:61], v42 offset:41280
	s_waitcnt lgkmcnt(4)
	v_mfma_f32_16x16x32_bf16 v[0:3], v[20:23], v[24:27], v[0:3]
	ds_read_b128 v[20:23], v66 offset:58624
	ds_read_b128 v[62:65], v42 offset:49984
	s_waitcnt lgkmcnt(5)
	v_mfma_f32_16x16x32_bf16 v[8:11], v[28:31], v[24:27], v[8:11]
	v_add_f32_e32 v28, v100, v67
	v_add_f32_e32 v67, v101, v28
	ds_read_b128 v[28:31], v42 offset:58688
	s_waitcnt lgkmcnt(5)
	v_mfma_f32_16x16x32_bf16 v[12:15], v[16:19], v[24:27], v[12:15]
	v_add_f32_e32 v16, v102, v67
	v_add_f32_e32 v67, v103, v16
	ds_read_b128 v[16:19], v66 offset:58688
	s_waitcnt lgkmcnt(3)
	v_mfma_f32_16x16x32_bf16 v[4:7], v[20:23], v[24:27], v[4:7]
	v_add_f32_e32 v20, v104, v67
	v_add_f32_e32 v20, v105, v20
	v_add_f32_e32 v20, v106, v20
	v_add_f32_e32 v20, v107, v20
	v_add_f32_e32 v20, v108, v20
	v_add_f32_e32 v20, v109, v20
	v_add_f32_e32 v20, v110, v20
	v_add_f32_e32 v24, v111, v20
	ds_read_b128 v[20:23], v42 offset:41344
	s_waitcnt lgkmcnt(3)
	v_mfma_f32_16x16x32_bf16 v[8:11], v[62:65], v[32:35], v[8:11]
	v_add_f32_e32 v62, v112, v24
	s_waitcnt lgkmcnt(2)
	v_mfma_f32_16x16x32_bf16 v[12:15], v[28:31], v[32:35], v[12:15]
	ds_read_b128 v[24:27], v43 offset:384
	ds_read_b128 v[28:31], v42 offset:50048
	v_mfma_f32_16x16x32_bf16 v[0:3], v[58:61], v[32:35], v[0:3]
	s_waitcnt lgkmcnt(3)
	v_mfma_f32_16x16x32_bf16 v[4:7], v[16:19], v[32:35], v[4:7]
	ds_read_b128 v[16:19], v42 offset:58752
	ds_read_b128 v[32:35], v43 offset:448
	ds_read_b128 v[58:61], v42 offset:41408
	v_add_f32_e32 v43, v113, v62
	s_waitcnt lgkmcnt(4)
	v_mfma_f32_16x16x32_bf16 v[0:3], v[20:23], v[24:27], v[0:3]
	ds_read_b128 v[20:23], v66 offset:58752
	ds_read_b128 v[62:65], v42 offset:50112
	ds_read_b128 v[66:69], v66 offset:58816
	s_waitcnt lgkmcnt(6)
	v_mfma_f32_16x16x32_bf16 v[8:11], v[28:31], v[24:27], v[8:11]
	v_add_f32_e32 v28, v114, v43
	v_add_f32_e32 v43, v115, v28
	ds_read_b128 v[28:31], v42 offset:58816
	s_waitcnt lgkmcnt(6)
	v_mfma_f32_16x16x32_bf16 v[16:19], v[16:19], v[24:27], v[12:15]
	s_nop 2
	v_add_f32_e32 v12, v116, v43
	v_add_f32_e32 v12, v117, v12
	s_waitcnt lgkmcnt(3)
	v_mfma_f32_16x16x32_bf16 v[20:23], v[20:23], v[24:27], v[4:7]
	s_nop 2
	v_add_f32_e32 v4, v118, v12
	v_add_f32_e32 v4, v119, v4
	v_add_f32_e32 v4, v120, v4
	v_mfma_f32_16x16x32_bf16 v[12:15], v[58:61], v[32:35], v[0:3]
	s_nop 2
	v_add_f32_e32 v0, v121, v4
	v_add_f32_e32 v0, v122, v0
	v_add_f32_e32 v0, v123, v0
	v_add_f32_e32 v0, v124, v0
	v_add_f32_e32 v0, v125, v0
	v_add_f32_e32 v0, v126, v0
	ds_bpermute_b32 v1, v88, v0
	s_waitcnt lgkmcnt(1)
	v_mfma_f32_16x16x32_bf16 v[4:7], v[28:31], v[32:35], v[16:19]
	s_waitcnt lgkmcnt(0)
	s_nop 1
	v_add_f32_e32 v16, v0, v1
	ds_bpermute_b32 v17, v89, v16
	v_mfma_f32_16x16x32_bf16 v[8:11], v[62:65], v[32:35], v[8:11]
	v_add_u32_e32 v18, v127, v55
	v_cmp_lt_i32_e32 vcc, v18, v45
	v_mfma_f32_16x16x32_bf16 v[0:3], v[66:69], v[32:35], v[20:23]
	s_and_saveexec_b64 s[14:15], vcc
	s_cbranch_execz .LBB0_1469
	s_waitcnt lgkmcnt(0)
	v_add_f32_e32 v17, v16, v17
	v_div_scale_f32 v16, s[22:23], v17, v17, 1.0
	v_rcp_f32_e32 v18, v16
	v_div_scale_f32 v19, vcc, 1.0, v17, 1.0
	s_lshl_b64 s[12:13], s[12:13], 17
	v_fma_f32 v20, -v16, v18, 1.0
	v_fmac_f32_e32 v18, v20, v18
	v_mul_f32_e32 v20, v19, v18
	v_fma_f32 v21, -v16, v20, v19
	v_fmac_f32_e32 v20, v21, v18
	v_fma_f32 v16, -v16, v20, v19
	v_div_fmas_f32 v16, v16, v18, v20
	s_lshl_b32 s11, s11, 2
	v_bfe_u32 v20, v53, 2, 2
	v_lshl_add_u64 v[18:19], v[40:41], 3, s[12:13]
	v_div_fixup_f32 v16, v16, v17, 1.0
	v_or3_b32 v18, v18, v20, s11
	v_lshlrev_b64 v[18:19], 2, v[18:19]
	v_pk_mul_f32 v[12:13], v[16:17], v[12:13] op_sel_hi:[0,1]
	v_and_or_b32 v18, v53, 3, v18
	v_cvt_pk_bf16_f32 v20, v12, v13
	v_pk_mul_f32 v[12:13], v[16:17], v[14:15] op_sel_hi:[0,1]
	v_readlane_b32 s12, v237, 40
	v_cvt_pk_bf16_f32 v21, v12, v13
	v_lshlrev_b64 v[12:13], 7, v[18:19]
	v_readlane_b32 s13, v237, 41
	v_mov_b32_e32 v45, v37
	v_cmp_eq_u32_e32 vcc, 0, v57
	v_lshl_add_u64 v[12:13], s[12:13], 0, v[12:13]
	v_lshl_add_u64 v[12:13], v[12:13], 0, v[44:45]
	global_store_dwordx2 v[12:13], v[20:21], off
	s_and_saveexec_b64 s[12:13], vcc
	s_cbranch_execz .LBB0_1468
	v_lshlrev_b64 v[14:15], 2, v[18:19]
	v_mul_f32_e32 v20, 0x3f317218, v36
	v_lshl_add_u64 v[18:19], s[2:3], 0, v[14:15]
	v_lshl_add_u64 v[14:15], s[8:9], 0, v[14:15]
	global_store_dword v[18:19], v20, off
	global_store_dword v[14:15], v17, off
	s_branch .LBB0_1468
